# XCC-local seam barriers: L1 invalidate issued before the arrival atomic (overlaps its latency with the wait); stacked
# speedup vs baseline: 1.0097x; 1.0097x over previous
; __device__ __forceinline__ unsigned xb_ld(unsigned* p)              { return __hip_atomic_load(p, __ATOMIC_RELAXED, __HIP_MEMORY_SCOPE_AGENT); }
; __device__ __forceinline__ unsigned xb_add(unsigned* p, unsigned v) { return __hip_atomic_fetch_add(p, v, __ATOMIC_RELAXED, __HIP_MEMORY_SCOPE_AGENT); }
; #define XB_SPIN(cond, bar) do { unsigned _sp = 0; while (cond) { __builtin_amdgcn_s_sleep(1); \
;     if ((++_sp & 255u) == 0u) { if (xb_ld(&(bar)[XB_TMO])) break; if (_sp > XB_SPIN_CAP) { atomicAdd(&(bar)[XB_TMO], 1u); break; } } } } while (0)
; #define x (arg_in(0))
; __device__ __forceinline__ void xcd_local_barrier(const XcdBarrier& b) {
;     ...
;     __syncthreads();
;     if (threadIdx.x == 0) {
;         unsigned* bar = b.bar;
;         __builtin_amdgcn_s_waitcnt(0);
;         unsigned nloc = b.st[0], nx = b.st[1];
;         if (nloc == 0u) { xcd_barrier_complete(bar, b.x, nloc, nx); b.st[0] = nloc; b.st[1] = nx; }
;         const unsigned old = xb_add(&bar[XB_XSUB2(b.x)], 1u);
;         const unsigned gen = old / nloc;
;         if (old + 1u == (gen + 1u) * nloc) xb_add(&bar[XB_XGEN2(b.x)], 1u);
;         else XB_SPIN(xb_ld(&bar[XB_XGEN2(b.x)]) == gen, bar);
;         __builtin_amdgcn_fence(__ATOMIC_ACQUIRE, "agent");
;         asm volatile("s_waitcnt vmcnt(0)" ::: "memory");
.LBB0_135:
	s_mov_b64 s[44:45], exec
	s_waitcnt lgkmcnt(0)
	v_mbcnt_lo_u32_b32 v1, s44, 0
	v_mbcnt_hi_u32_b32 v1, s45, v1
	v_cmp_eq_u32_e32 vcc, 0, v1
	s_and_saveexec_b64 s[36:37], vcc
	s_cbranch_execz .LBB0_137
	s_bcnt1_i32_b64 s14, s[44:45]
	v_mov_b32_e32 v2, s14
	v_readlane_b32 s14, v253, 50
	v_readlane_b32 s15, v253, 51
	s_nop 4
	buffer_inv sc1
	global_atomic_add v2, v129, v2, s[14:15] sc0

; __device__ __forceinline__ unsigned xb_ld(unsigned* p)              { return __hip_atomic_load(p, __ATOMIC_RELAXED, __HIP_MEMORY_SCOPE_AGENT); }
; __device__ __forceinline__ unsigned xb_add(unsigned* p, unsigned v) { return __hip_atomic_fetch_add(p, v, __ATOMIC_RELAXED, __HIP_MEMORY_SCOPE_AGENT); }
; #define XB_SPIN(cond, bar) do { unsigned _sp = 0; while (cond) { __builtin_amdgcn_s_sleep(1); \
;     if ((++_sp & 255u) == 0u) { if (xb_ld(&(bar)[XB_TMO])) break; if (_sp > XB_SPIN_CAP) { atomicAdd(&(bar)[XB_TMO], 1u); break; } } } } while (0)
; #define x (arg_in(0))
; __device__ __forceinline__ void xcd_local_barrier(const XcdBarrier& b) {
;     ...
;         if (old + 1u == (gen + 1u) * nloc) xb_add(&bar[XB_XGEN2(b.x)], 1u);
;         else XB_SPIN(xb_ld(&bar[XB_XGEN2(b.x)]) == gen, bar);
;         __builtin_amdgcn_fence(__ATOMIC_ACQUIRE, "agent");
;         asm volatile("s_waitcnt vmcnt(0)" ::: "memory");
.LBB0_151:
	s_or_b64 exec, exec, s[44:45]
	s_waitcnt vmcnt(0)
	s_waitcnt vmcnt(0)

; __device__ __forceinline__ unsigned xb_ld(unsigned* p)              { return __hip_atomic_load(p, __ATOMIC_RELAXED, __HIP_MEMORY_SCOPE_AGENT); }
; __device__ __forceinline__ unsigned xb_add(unsigned* p, unsigned v) { return __hip_atomic_fetch_add(p, v, __ATOMIC_RELAXED, __HIP_MEMORY_SCOPE_AGENT); }
; #define XB_SPIN(cond, bar) do { unsigned _sp = 0; while (cond) { __builtin_amdgcn_s_sleep(1); \
;     if ((++_sp & 255u) == 0u) { if (xb_ld(&(bar)[XB_TMO])) break; if (_sp > XB_SPIN_CAP) { atomicAdd(&(bar)[XB_TMO], 1u); break; } } } } while (0)
; #define x (arg_in(0))
; __device__ __forceinline__ void xcd_local_barrier(const XcdBarrier& b) {
;     ...
;     __syncthreads();
;     if (threadIdx.x == 0) {
;         unsigned* bar = b.bar;
;         __builtin_amdgcn_s_waitcnt(0);
;         unsigned nloc = b.st[0], nx = b.st[1];
;         if (nloc == 0u) { xcd_barrier_complete(bar, b.x, nloc, nx); b.st[0] = nloc; b.st[1] = nx; }
;         const unsigned old = xb_add(&bar[XB_XSUB2(b.x)], 1u);
;         const unsigned gen = old / nloc;
;         if (old + 1u == (gen + 1u) * nloc) xb_add(&bar[XB_XGEN2(b.x)], 1u);
;         else XB_SPIN(xb_ld(&bar[XB_XGEN2(b.x)]) == gen, bar);
;         __builtin_amdgcn_fence(__ATOMIC_ACQUIRE, "agent");
;         asm volatile("s_waitcnt vmcnt(0)" ::: "memory");
.LBB0_484:
	s_mov_b64 s[42:43], exec
	s_waitcnt lgkmcnt(0)
	v_mbcnt_lo_u32_b32 v1, s42, 0
	v_mbcnt_hi_u32_b32 v1, s43, v1
	v_cmp_eq_u32_e32 vcc, 0, v1
	s_and_saveexec_b64 s[36:37], vcc
	s_cbranch_execz .LBB0_486
	s_bcnt1_i32_b64 s14, s[42:43]
	v_mov_b32_e32 v2, s14
	v_readlane_b32 s14, v253, 50
	v_readlane_b32 s15, v253, 51
	s_nop 4
	buffer_inv sc1
	global_atomic_add v2, v129, v2, s[14:15] sc0

; __device__ __forceinline__ unsigned xb_ld(unsigned* p)              { return __hip_atomic_load(p, __ATOMIC_RELAXED, __HIP_MEMORY_SCOPE_AGENT); }
; __device__ __forceinline__ unsigned xb_add(unsigned* p, unsigned v) { return __hip_atomic_fetch_add(p, v, __ATOMIC_RELAXED, __HIP_MEMORY_SCOPE_AGENT); }
; #define XB_SPIN(cond, bar) do { unsigned _sp = 0; while (cond) { __builtin_amdgcn_s_sleep(1); \
;     if ((++_sp & 255u) == 0u) { if (xb_ld(&(bar)[XB_TMO])) break; if (_sp > XB_SPIN_CAP) { atomicAdd(&(bar)[XB_TMO], 1u); break; } } } } while (0)
; #define x (arg_in(0))
; __device__ __forceinline__ void xcd_local_barrier(const XcdBarrier& b) {
;     ...
;         if (old + 1u == (gen + 1u) * nloc) xb_add(&bar[XB_XGEN2(b.x)], 1u);
;         else XB_SPIN(xb_ld(&bar[XB_XGEN2(b.x)]) == gen, bar);
;         __builtin_amdgcn_fence(__ATOMIC_ACQUIRE, "agent");
;         asm volatile("s_waitcnt vmcnt(0)" ::: "memory");
.LBB0_500:
	s_or_b64 exec, exec, s[42:43]
	s_waitcnt vmcnt(0)
	s_waitcnt vmcnt(0)

; __device__ __forceinline__ unsigned xb_add(unsigned* p, unsigned v) { return __hip_atomic_fetch_add(p, v, __ATOMIC_RELAXED, __HIP_MEMORY_SCOPE_AGENT); }
; #define x (arg_in(0))
; __device__ __forceinline__ void xcd_local_barrier(const XcdBarrier& b) {
;     ...
;     __syncthreads();
;     if (threadIdx.x == 0) {
;         unsigned* bar = b.bar;
;         __builtin_amdgcn_s_waitcnt(0);
;         unsigned nloc = b.st[0], nx = b.st[1];
;         if (nloc == 0u) { xcd_barrier_complete(bar, b.x, nloc, nx); b.st[0] = nloc; b.st[1] = nx; }
;         const unsigned old = xb_add(&bar[XB_XSUB2(b.x)], 1u);
;         const unsigned gen = old / nloc;
;         if (old + 1u == (gen + 1u) * nloc) xb_add(&bar[XB_XGEN2(b.x)], 1u);
.LBB0_690:
	s_mov_b64 s[42:43], exec
	s_waitcnt lgkmcnt(0)
	v_mbcnt_lo_u32_b32 v1, s42, 0
	v_mbcnt_hi_u32_b32 v1, s43, v1
	v_cmp_eq_u32_e32 vcc, 0, v1
	s_and_saveexec_b64 s[36:37], vcc
	s_cbranch_execz .LBB0_692
	s_bcnt1_i32_b64 s8, s[42:43]
	v_readlane_b32 s14, v253, 50
	v_mov_b32_e32 v2, s8
	v_readlane_b32 s15, v253, 51
	s_nop 4
	buffer_inv sc1
	global_atomic_add v2, v129, v2, s[14:15] sc0
